# attention map-1 epilogue: per-load progressive vmcnt waits on the 17 parked-O / Q loads instead of one vmcnt(0)
# baseline (speedup 1.0000x reference)
.LBB0_527:
	s_mov_b32 s100, 0x1000
	s_mov_b32 s101, 0
	v_lshl_add_u64 v[160:161], s[100:101], 0, v[136:137]
	v_lshl_add_u64 v[162:163], s[100:101], 1, v[136:137]
	v_lshl_add_u64 v[164:165], s[100:101], 0, v[162:163]
	global_load_dwordx4 v[98:101], v[136:137], off offset:3072
	global_load_dwordx4 v[94:97], v[136:137], off offset:2048
	global_load_dwordx4 v[82:85], v[136:137], off offset:1024
	global_load_dwordx4 v[70:73], v[136:137], off
	global_load_dwordx4 v[118:121], v[160:161], off offset:3072
	global_load_dwordx4 v[110:113], v[160:161], off offset:2048
	global_load_dwordx4 v[106:109], v[160:161], off offset:1024
	global_load_dwordx4 v[102:105], v[160:161], off
	global_load_dwordx4 v[114:117], v[162:163], off offset:3072
	global_load_dwordx4 v[122:125], v[162:163], off offset:2048
	global_load_dwordx4 v[130:133], v[162:163], off offset:1024
	global_load_dwordx4 v[126:129], v[162:163], off
	global_load_dwordx4 v[78:81], v[164:165], off offset:2048
	global_load_dwordx4 v[86:89], v[164:165], off offset:1024
	global_load_dwordx4 v[90:93], v[164:165], off
	global_load_dwordx4 v[74:77], v[164:165], off offset:3072
	v_mul_f32_e32 v152, s19, v0
	global_load_dwordx4 v[66:69], v[148:149], off
	s_waitcnt vmcnt(16)
	v_pk_fma_f32 v[168:169], v[62:63], v[152:153], v[98:99] op_sel_hi:[1,0,1] neg_lo:[1,0,0] neg_hi:[1,0,0]
	s_waitcnt vmcnt(15)
	v_pk_fma_f32 v[164:165], v[58:59], v[152:153], v[94:95] op_sel_hi:[1,0,1] neg_lo:[1,0,0] neg_hi:[1,0,0]
	s_waitcnt vmcnt(14)
	v_pk_fma_f32 v[160:161], v[54:55], v[152:153], v[82:83] op_sel_hi:[1,0,1] neg_lo:[1,0,0] neg_hi:[1,0,0]
	s_waitcnt vmcnt(13)
	v_pk_fma_f32 v[156:157], v[50:51], v[152:153], v[70:71] op_sel_hi:[1,0,1] neg_lo:[1,0,0] neg_hi:[1,0,0]
	v_pk_fma_f32 v[154:155], v[52:53], v[152:153], v[72:73] op_sel_hi:[1,0,1] neg_lo:[1,0,0] neg_hi:[1,0,0]
	v_mul_f32_e32 v70, v157, v157
	v_pk_fma_f32 v[70:71], v[156:157], v[156:157], v[70:71] op_sel_hi:[1,1,0]
	v_mul_f32_e32 v72, v155, v155
	v_pk_fma_f32 v[70:71], v[154:155], v[154:155], v[70:71]
	v_pk_fma_f32 v[158:159], v[56:57], v[152:153], v[84:85] op_sel_hi:[1,0,1] neg_lo:[1,0,0] neg_hi:[1,0,0]
	v_pk_add_f32 v[162:163], v[72:73], v[70:71] op_sel_hi:[0,1]
	v_pk_fma_f32 v[82:83], v[160:161], v[160:161], v[162:163]
	v_mul_f32_e32 v84, v161, v161
	v_pk_add_f32 v[82:83], v[84:85], v[82:83] op_sel_hi:[0,1]
	v_pk_fma_f32 v[82:83], v[158:159], v[158:159], v[82:83]
	v_mul_f32_e32 v84, v159, v159
	v_pk_add_f32 v[166:167], v[84:85], v[82:83] op_sel_hi:[0,1]
	v_pk_fma_f32 v[162:163], v[60:61], v[152:153], v[96:97] op_sel_hi:[1,0,1] neg_lo:[1,0,0] neg_hi:[1,0,0]
	v_pk_fma_f32 v[94:95], v[164:165], v[164:165], v[166:167]
	v_mul_f32_e32 v96, v165, v165
	v_pk_add_f32 v[94:95], v[96:97], v[94:95] op_sel_hi:[0,1]
	v_pk_fma_f32 v[94:95], v[162:163], v[162:163], v[94:95]
	v_mul_f32_e32 v96, v163, v163
	v_pk_add_f32 v[170:171], v[96:97], v[94:95] op_sel_hi:[0,1]
	v_pk_fma_f32 v[166:167], v[64:65], v[152:153], v[100:101] op_sel_hi:[1,0,1] neg_lo:[1,0,0] neg_hi:[1,0,0]
	v_pk_fma_f32 v[98:99], v[168:169], v[168:169], v[170:171]
	v_mul_f32_e32 v100, v169, v169
	v_pk_add_f32 v[98:99], v[100:101], v[98:99] op_sel_hi:[0,1]
	v_pk_fma_f32 v[98:99], v[166:167], v[166:167], v[98:99]
	v_mul_f32_e32 v100, v167, v167
	v_pk_add_f32 v[174:175], v[100:101], v[98:99] op_sel_hi:[0,1]
	s_waitcnt vmcnt(9)
	v_pk_fma_f32 v[172:173], v[34:35], v[152:153], v[102:103] op_sel_hi:[1,0,1] neg_lo:[1,0,0] neg_hi:[1,0,0]
	v_pk_fma_f32 v[170:171], v[36:37], v[152:153], v[104:105] op_sel_hi:[1,0,1] neg_lo:[1,0,0] neg_hi:[1,0,0]
	v_pk_fma_f32 v[102:103], v[172:173], v[172:173], v[174:175]
	v_mul_f32_e32 v104, v173, v173
	v_pk_add_f32 v[102:103], v[104:105], v[102:103] op_sel_hi:[0,1]
	v_pk_fma_f32 v[102:103], v[170:171], v[170:171], v[102:103]
	v_mul_f32_e32 v104, v171, v171
	v_pk_add_f32 v[178:179], v[104:105], v[102:103] op_sel_hi:[0,1]
	v_pk_fma_f32 v[176:177], v[38:39], v[152:153], v[106:107] op_sel_hi:[1,0,1] neg_lo:[1,0,0] neg_hi:[1,0,0]
	global_load_dwordx4 v[70:73], v[148:149], off offset:32
	v_pk_fma_f32 v[174:175], v[40:41], v[152:153], v[108:109] op_sel_hi:[1,0,1] neg_lo:[1,0,0] neg_hi:[1,0,0]
	v_pk_fma_f32 v[106:107], v[176:177], v[176:177], v[178:179]
	v_mul_f32_e32 v108, v177, v177
	v_pk_add_f32 v[106:107], v[108:109], v[106:107] op_sel_hi:[0,1]
	v_pk_fma_f32 v[106:107], v[174:175], v[174:175], v[106:107]
	v_mul_f32_e32 v108, v175, v175
	global_load_dwordx4 v[82:85], v[148:149], off offset:64
	global_load_dwordx4 v[94:97], v[148:149], off offset:96
	v_pk_add_f32 v[182:183], v[108:109], v[106:107] op_sel_hi:[0,1]
	v_pk_fma_f32 v[180:181], v[42:43], v[152:153], v[110:111] op_sel_hi:[1,0,1] neg_lo:[1,0,0] neg_hi:[1,0,0]
	v_pk_fma_f32 v[178:179], v[44:45], v[152:153], v[112:113] op_sel_hi:[1,0,1] neg_lo:[1,0,0] neg_hi:[1,0,0]
	v_pk_fma_f32 v[110:111], v[180:181], v[180:181], v[182:183]
	v_mul_f32_e32 v112, v181, v181
	v_pk_add_f32 v[110:111], v[112:113], v[110:111] op_sel_hi:[0,1]
	v_pk_fma_f32 v[110:111], v[178:179], v[178:179], v[110:111]
	v_mul_f32_e32 v112, v179, v179
	v_pk_add_f32 v[186:187], v[112:113], v[110:111] op_sel_hi:[0,1]
	v_pk_fma_f32 v[184:185], v[46:47], v[152:153], v[118:119] op_sel_hi:[1,0,1] neg_lo:[1,0,0] neg_hi:[1,0,0]
	v_pk_fma_f32 v[182:183], v[48:49], v[152:153], v[120:121] op_sel_hi:[1,0,1] neg_lo:[1,0,0] neg_hi:[1,0,0]
	v_pk_fma_f32 v[118:119], v[184:185], v[184:185], v[186:187]
	v_mul_f32_e32 v120, v185, v185
	global_load_dwordx4 v[98:101], v[148:149], off offset:128
	global_load_dwordx4 v[102:105], v[148:149], off offset:160
	v_pk_add_f32 v[118:119], v[120:121], v[118:119] op_sel_hi:[0,1]
	v_pk_fma_f32 v[118:119], v[182:183], v[182:183], v[118:119]
	v_mul_f32_e32 v120, v183, v183
	v_pk_add_f32 v[190:191], v[120:121], v[118:119] op_sel_hi:[0,1]
	s_waitcnt vmcnt(10)
	v_pk_fma_f32 v[188:189], v[18:19], v[152:153], v[126:127] op_sel_hi:[1,0,1] neg_lo:[1,0,0] neg_hi:[1,0,0]
	v_pk_fma_f32 v[186:187], v[20:21], v[152:153], v[128:129] op_sel_hi:[1,0,1] neg_lo:[1,0,0] neg_hi:[1,0,0]
	v_pk_fma_f32 v[126:127], v[188:189], v[188:189], v[190:191]
	v_mul_f32_e32 v128, v189, v189
	v_pk_add_f32 v[126:127], v[128:129], v[126:127] op_sel_hi:[0,1]
	v_pk_fma_f32 v[126:127], v[186:187], v[186:187], v[126:127]
	v_mul_f32_e32 v128, v187, v187
	global_load_dwordx4 v[106:109], v[148:149], off offset:192
	global_load_dwordx4 v[110:113], v[148:149], off offset:224
	v_pk_add_f32 v[194:195], v[128:129], v[126:127] op_sel_hi:[0,1]
	v_pk_fma_f32 v[192:193], v[22:23], v[152:153], v[130:131] op_sel_hi:[1,0,1] neg_lo:[1,0,0] neg_hi:[1,0,0]
	v_pk_fma_f32 v[190:191], v[24:25], v[152:153], v[132:133] op_sel_hi:[1,0,1] neg_lo:[1,0,0] neg_hi:[1,0,0]
	v_pk_fma_f32 v[130:131], v[192:193], v[192:193], v[194:195]
	v_mul_f32_e32 v132, v193, v193
	v_pk_add_f32 v[130:131], v[132:133], v[130:131] op_sel_hi:[0,1]
	v_pk_fma_f32 v[130:131], v[190:191], v[190:191], v[130:131]
	v_mul_f32_e32 v132, v191, v191
	v_pk_add_f32 v[198:199], v[132:133], v[130:131] op_sel_hi:[0,1]
	v_pk_fma_f32 v[196:197], v[26:27], v[152:153], v[122:123] op_sel_hi:[1,0,1] neg_lo:[1,0,0] neg_hi:[1,0,0]
	v_pk_fma_f32 v[194:195], v[28:29], v[152:153], v[124:125] op_sel_hi:[1,0,1] neg_lo:[1,0,0] neg_hi:[1,0,0]
	v_pk_fma_f32 v[122:123], v[196:197], v[196:197], v[198:199]
	v_mul_f32_e32 v124, v197, v197
	global_load_dwordx4 v[118:121], v[148:149], off offset:256
	global_load_dwordx4 v[126:129], v[148:149], off offset:288
	v_pk_add_f32 v[122:123], v[124:125], v[122:123] op_sel_hi:[0,1]
	v_pk_fma_f32 v[122:123], v[194:195], v[194:195], v[122:123]
	v_mul_f32_e32 v124, v195, v195
	v_pk_add_f32 v[202:203], v[124:125], v[122:123] op_sel_hi:[0,1]
	v_pk_fma_f32 v[200:201], v[30:31], v[152:153], v[114:115] op_sel_hi:[1,0,1] neg_lo:[1,0,0] neg_hi:[1,0,0]
	v_pk_fma_f32 v[198:199], v[32:33], v[152:153], v[116:117] op_sel_hi:[1,0,1] neg_lo:[1,0,0] neg_hi:[1,0,0]
	v_pk_fma_f32 v[114:115], v[200:201], v[200:201], v[202:203]
	v_mul_f32_e32 v116, v201, v201
	v_pk_add_f32 v[114:115], v[116:117], v[114:115] op_sel_hi:[0,1]
	v_pk_fma_f32 v[114:115], v[198:199], v[198:199], v[114:115]
	v_mul_f32_e32 v116, v199, v199
	global_load_dwordx4 v[130:133], v[148:149], off offset:320
	global_load_dwordx4 v[122:125], v[148:149], off offset:352
	v_pk_add_f32 v[220:221], v[116:117], v[114:115] op_sel_hi:[0,1]
	s_waitcnt vmcnt(13)
	v_pk_fma_f32 v[222:223], v[2:3], v[152:153], v[90:91] op_sel_hi:[1,0,1] neg_lo:[1,0,0] neg_hi:[1,0,0]
	v_pk_fma_f32 v[202:203], v[4:5], v[152:153], v[92:93] op_sel_hi:[1,0,1] neg_lo:[1,0,0] neg_hi:[1,0,0]
	v_pk_fma_f32 v[90:91], v[222:223], v[222:223], v[220:221]
	v_mul_f32_e32 v92, v223, v223
	v_pk_add_f32 v[90:91], v[92:93], v[90:91] op_sel_hi:[0,1]
	v_pk_fma_f32 v[90:91], v[202:203], v[202:203], v[90:91]
	v_mul_f32_e32 v92, v203, v203
	v_pk_add_f32 v[220:221], v[92:93], v[90:91] op_sel_hi:[0,1]
	v_pk_fma_f32 v[226:227], v[6:7], v[152:153], v[86:87] op_sel_hi:[1,0,1] neg_lo:[1,0,0] neg_hi:[1,0,0]
	v_pk_fma_f32 v[224:225], v[8:9], v[152:153], v[88:89] op_sel_hi:[1,0,1] neg_lo:[1,0,0] neg_hi:[1,0,0]
	v_pk_fma_f32 v[86:87], v[226:227], v[226:227], v[220:221]
	v_mul_f32_e32 v88, v227, v227
	global_load_dwordx4 v[114:117], v[148:149], off offset:384
	global_load_dwordx4 v[90:93], v[148:149], off offset:416
	v_pk_add_f32 v[86:87], v[88:89], v[86:87] op_sel_hi:[0,1]
	v_pk_fma_f32 v[86:87], v[224:225], v[224:225], v[86:87]
	v_mul_f32_e32 v88, v225, v225
	v_pk_add_f32 v[220:221], v[88:89], v[86:87] op_sel_hi:[0,1]
	v_pk_fma_f32 v[230:231], v[10:11], v[152:153], v[78:79] op_sel_hi:[1,0,1] neg_lo:[1,0,0] neg_hi:[1,0,0]
	v_pk_fma_f32 v[228:229], v[12:13], v[152:153], v[80:81] op_sel_hi:[1,0,1] neg_lo:[1,0,0] neg_hi:[1,0,0]
	v_pk_fma_f32 v[78:79], v[230:231], v[230:231], v[220:221]
	v_mul_f32_e32 v80, v231, v231
	v_pk_add_f32 v[78:79], v[80:81], v[78:79] op_sel_hi:[0,1]
	v_pk_fma_f32 v[78:79], v[228:229], v[228:229], v[78:79]
	v_mul_f32_e32 v80, v229, v229
	global_load_dwordx4 v[86:89], v[148:149], off offset:448
	v_pk_add_f32 v[220:221], v[80:81], v[78:79] op_sel_hi:[0,1]
	s_waitcnt vmcnt(15)
	v_pk_fma_f32 v[74:75], v[14:15], v[152:153], v[74:75] op_sel_hi:[1,0,1] neg_lo:[1,0,0] neg_hi:[1,0,0]
	v_pk_fma_f32 v[76:77], v[16:17], v[152:153], v[76:77] op_sel_hi:[1,0,1] neg_lo:[1,0,0] neg_hi:[1,0,0]
	v_pk_fma_f32 v[152:153], v[74:75], v[74:75], v[220:221]
	v_mul_f32_e32 v220, v75, v75
	v_pk_add_f32 v[152:153], v[220:221], v[152:153] op_sel_hi:[0,1]
	global_load_dwordx4 v[78:81], v[148:149], off offset:480
	v_pk_fma_f32 v[152:153], v[76:77], v[76:77], v[152:153]
	v_mul_f32_e32 v220, v77, v77
	v_pk_add_f32 v[152:153], v[220:221], v[152:153] op_sel_hi:[0,1]
	v_mov_b32_e32 v153, v152
	s_nop 1
	v_permlane32_swap_b32_e32 v152, v153
	v_add_f32_e32 v152, v152, v153
	v_fmamk_f32 v152, v152, 0x3c000000, v240
	v_cmp_gt_f32_e32 vcc, s31, v152
	v_mul_f32_e32 v153, 0x4f800000, v152
	s_nop 0
	v_cndmask_b32_e32 v152, v152, v153, vcc
	v_sqrt_f32_e32 v153, v152
	s_nop 0
	v_add_u32_e32 v219, -1, v153
	v_fma_f32 v220, -v219, v153, v152
	v_cmp_ge_f32_e64 s[44:45], 0, v220
	v_add_u32_e32 v220, 1, v153
	s_nop 0
	v_cndmask_b32_e64 v219, v153, v219, s[44:45]
	v_fma_f32 v153, -v220, v153, v152
	v_cmp_lt_f32_e64 s[44:45], 0, v153
	s_nop 1
	v_cndmask_b32_e64 v153, v219, v220, s[44:45]
	v_mul_f32_e32 v219, 0x37800000, v153
	v_cndmask_b32_e32 v153, v153, v219, vcc
	v_cmp_class_f32_e32 vcc, v152, v241
	s_nop 1
	v_cndmask_b32_e32 v152, v153, v152, vcc
	v_div_scale_f32 v153, s[24:25], v152, v152, v204
	v_rcp_f32_e32 v219, v153
	s_nop 0
	v_fma_f32 v220, -v153, v219, 1.0
	v_fmac_f32_e32 v219, v220, v219
	v_div_scale_f32 v220, vcc, v204, v152, v204
	v_mul_f32_e32 v221, v220, v219
	v_fma_f32 v232, -v153, v221, v220
	v_fmac_f32_e32 v221, v232, v219
	v_fma_f32 v153, -v153, v221, v220
	v_div_fmas_f32 v153, v153, v219, v221
	v_div_fixup_f32 v152, v153, v152, v204
	v_pk_mul_f32 v[156:157], v[156:157], v[152:153] op_sel_hi:[1,0]
	v_pk_mul_f32 v[154:155], v[154:155], v[152:153] op_sel_hi:[1,0]
	s_waitcnt vmcnt(15)
	v_pk_mul_f32 v[66:67], v[66:67], v[156:157]
	v_pk_mul_f32 v[68:69], v[68:69], v[154:155]
	v_cvt_pk_bf16_f32 v66, v66, v67
	v_cvt_pk_bf16_f32 v67, v68, v69
	v_mbcnt_lo_u32_b32 v248, -1, 0
	v_mbcnt_hi_u32_b32 v248, -1, v248
	v_lshrrev_b32_e32 v248, 5, v248
	v_lshlrev_b32_e32 v248, 3, v248
	v_mov_b32_e32 v249, 0
	v_lshl_add_u64 v[246:247], v[150:151], 0, v[248:249]
	v_pk_mul_f32 v[242:243], v[160:161], v[152:153] op_sel_hi:[1,0]
	v_pk_mul_f32 v[244:245], v[158:159], v[152:153] op_sel_hi:[1,0]
	s_waitcnt vmcnt(0)
	v_pk_mul_f32 v[242:243], v[70:71], v[242:243]
	v_pk_mul_f32 v[244:245], v[72:73], v[244:245]
	v_cvt_pk_bf16_f32 v68, v242, v243
	v_cvt_pk_bf16_f32 v69, v244, v245
	s_nop 1
	v_permlane32_swap_b32_e32 v66, v68
	v_permlane32_swap_b32_e32 v67, v69
	global_store_dwordx4 v[246:247], v[66:69], off
	s_nop 1
	v_pk_mul_f32 v[66:67], v[164:165], v[152:153] op_sel_hi:[1,0]
	v_pk_mul_f32 v[68:69], v[162:163], v[152:153] op_sel_hi:[1,0]
	v_pk_mul_f32 v[66:67], v[82:83], v[66:67]
	v_pk_mul_f32 v[68:69], v[84:85], v[68:69]
	v_cvt_pk_bf16_f32 v66, v66, v67
	v_cvt_pk_bf16_f32 v67, v68, v69
	v_pk_mul_f32 v[242:243], v[168:169], v[152:153] op_sel_hi:[1,0]
	v_pk_mul_f32 v[244:245], v[166:167], v[152:153] op_sel_hi:[1,0]
	v_pk_mul_f32 v[242:243], v[94:95], v[242:243]
	v_pk_mul_f32 v[244:245], v[96:97], v[244:245]
	v_cvt_pk_bf16_f32 v68, v242, v243
	v_cvt_pk_bf16_f32 v69, v244, v245
	s_nop 1
	v_permlane32_swap_b32_e32 v66, v68
	v_permlane32_swap_b32_e32 v67, v69
	global_store_dwordx4 v[246:247], v[66:69], off offset:32
	s_nop 1
	v_pk_mul_f32 v[66:67], v[172:173], v[152:153] op_sel_hi:[1,0]
	v_pk_mul_f32 v[68:69], v[170:171], v[152:153] op_sel_hi:[1,0]
	v_pk_mul_f32 v[66:67], v[66:67], v[98:99]
	v_pk_mul_f32 v[68:69], v[68:69], v[100:101]
	v_cvt_pk_bf16_f32 v66, v66, v67
	v_cvt_pk_bf16_f32 v67, v68, v69
	v_pk_mul_f32 v[242:243], v[176:177], v[152:153] op_sel_hi:[1,0]
	v_pk_mul_f32 v[244:245], v[174:175], v[152:153] op_sel_hi:[1,0]
	v_pk_mul_f32 v[242:243], v[242:243], v[102:103]
	v_pk_mul_f32 v[244:245], v[244:245], v[104:105]
	v_cvt_pk_bf16_f32 v68, v242, v243
	v_cvt_pk_bf16_f32 v69, v244, v245
	s_nop 1
	v_permlane32_swap_b32_e32 v66, v68
	v_permlane32_swap_b32_e32 v67, v69
	global_store_dwordx4 v[246:247], v[66:69], off offset:64
	s_nop 1
	v_pk_mul_f32 v[66:67], v[180:181], v[152:153] op_sel_hi:[1,0]
	v_pk_mul_f32 v[68:69], v[178:179], v[152:153] op_sel_hi:[1,0]
	v_pk_mul_f32 v[66:67], v[66:67], v[106:107]
	v_pk_mul_f32 v[68:69], v[68:69], v[108:109]
	v_cvt_pk_bf16_f32 v66, v66, v67
	v_cvt_pk_bf16_f32 v67, v68, v69
	v_pk_mul_f32 v[242:243], v[184:185], v[152:153] op_sel_hi:[1,0]
	v_pk_mul_f32 v[244:245], v[182:183], v[152:153] op_sel_hi:[1,0]
	v_pk_mul_f32 v[242:243], v[242:243], v[110:111]
	v_pk_mul_f32 v[244:245], v[244:245], v[112:113]
	v_cvt_pk_bf16_f32 v68, v242, v243
	v_cvt_pk_bf16_f32 v69, v244, v245
	s_nop 1
	v_permlane32_swap_b32_e32 v66, v68
	v_permlane32_swap_b32_e32 v67, v69
	global_store_dwordx4 v[246:247], v[66:69], off offset:96
	s_nop 1
	v_pk_mul_f32 v[66:67], v[188:189], v[152:153] op_sel_hi:[1,0]
	v_pk_mul_f32 v[68:69], v[186:187], v[152:153] op_sel_hi:[1,0]
	v_pk_mul_f32 v[66:67], v[66:67], v[118:119]
	v_pk_mul_f32 v[68:69], v[68:69], v[120:121]
	v_cvt_pk_bf16_f32 v66, v66, v67
	v_cvt_pk_bf16_f32 v67, v68, v69
	v_pk_mul_f32 v[242:243], v[192:193], v[152:153] op_sel_hi:[1,0]
	v_pk_mul_f32 v[244:245], v[190:191], v[152:153] op_sel_hi:[1,0]
	v_pk_mul_f32 v[242:243], v[242:243], v[126:127]
	v_pk_mul_f32 v[244:245], v[244:245], v[128:129]
	v_cvt_pk_bf16_f32 v68, v242, v243
	v_cvt_pk_bf16_f32 v69, v244, v245
	s_nop 1
	v_permlane32_swap_b32_e32 v66, v68
	v_permlane32_swap_b32_e32 v67, v69
	global_store_dwordx4 v[246:247], v[66:69], off offset:128
	s_nop 1
	v_pk_mul_f32 v[66:67], v[196:197], v[152:153] op_sel_hi:[1,0]
	v_pk_mul_f32 v[68:69], v[194:195], v[152:153] op_sel_hi:[1,0]
	v_pk_mul_f32 v[66:67], v[66:67], v[130:131]
	v_pk_mul_f32 v[68:69], v[68:69], v[132:133]
	v_cvt_pk_bf16_f32 v66, v66, v67
	v_cvt_pk_bf16_f32 v67, v68, v69
	v_pk_mul_f32 v[242:243], v[200:201], v[152:153] op_sel_hi:[1,0]
	v_pk_mul_f32 v[244:245], v[198:199], v[152:153] op_sel_hi:[1,0]
	v_pk_mul_f32 v[242:243], v[242:243], v[122:123]
	v_pk_mul_f32 v[244:245], v[244:245], v[124:125]
	v_cvt_pk_bf16_f32 v68, v242, v243
	v_cvt_pk_bf16_f32 v69, v244, v245
	s_nop 1
	v_permlane32_swap_b32_e32 v66, v68
	v_permlane32_swap_b32_e32 v67, v69
	global_store_dwordx4 v[246:247], v[66:69], off offset:160
	s_nop 1
	v_pk_mul_f32 v[66:67], v[222:223], v[152:153] op_sel_hi:[1,0]
	v_pk_mul_f32 v[68:69], v[202:203], v[152:153] op_sel_hi:[1,0]
	v_pk_mul_f32 v[66:67], v[66:67], v[114:115]
	v_pk_mul_f32 v[68:69], v[68:69], v[116:117]
	v_cvt_pk_bf16_f32 v66, v66, v67
	v_cvt_pk_bf16_f32 v67, v68, v69
	v_pk_mul_f32 v[242:243], v[226:227], v[152:153] op_sel_hi:[1,0]
	v_pk_mul_f32 v[244:245], v[224:225], v[152:153] op_sel_hi:[1,0]
	v_pk_mul_f32 v[242:243], v[242:243], v[90:91]
	v_pk_mul_f32 v[244:245], v[244:245], v[92:93]
	v_cvt_pk_bf16_f32 v68, v242, v243
	v_cvt_pk_bf16_f32 v69, v244, v245
	s_nop 1
	v_permlane32_swap_b32_e32 v66, v68
	v_permlane32_swap_b32_e32 v67, v69
	global_store_dwordx4 v[246:247], v[66:69], off offset:192
	s_nop 1
	v_pk_mul_f32 v[66:67], v[230:231], v[152:153] op_sel_hi:[1,0]
	v_pk_mul_f32 v[68:69], v[228:229], v[152:153] op_sel_hi:[1,0]
	v_pk_mul_f32 v[66:67], v[66:67], v[86:87]
	v_pk_mul_f32 v[68:69], v[68:69], v[88:89]
	v_cvt_pk_bf16_f32 v66, v66, v67
	v_cvt_pk_bf16_f32 v67, v68, v69
	v_pk_mul_f32 v[242:243], v[74:75], v[152:153] op_sel_hi:[1,0]
	v_pk_mul_f32 v[244:245], v[76:77], v[152:153] op_sel_hi:[1,0]
	v_pk_mul_f32 v[242:243], v[242:243], v[78:79]
	v_pk_mul_f32 v[244:245], v[244:245], v[80:81]
	v_cvt_pk_bf16_f32 v68, v242, v243
	v_cvt_pk_bf16_f32 v69, v244, v245
	s_nop 1
	v_permlane32_swap_b32_e32 v66, v68
	v_permlane32_swap_b32_e32 v67, v69
	global_store_dwordx4 v[246:247], v[66:69], off offset:224
	s_nop 1
	s_cbranch_execnz .LBB0_503
